# rowop<4> kind 2: the 16 serialized nt loads of the o rows issued together right after their row pointers (recounted vmcnt)
# speedup vs baseline: 1.0186x; 1.0111x over previous
.LBB0_28:
	s_movk_i32 s0, 0x4000
	v_cmp_gt_i32_e32 vcc, s0, v104
	s_or_b64 s[0:1], s[6:7], vcc
	s_and_saveexec_b64 s[8:9], s[0:1]
	s_cbranch_execz .LBB0_27
	s_movk_i32 s0, 0x4000
	v_cmp_gt_i32_e32 vcc, s0, v104
	v_min_i32_e32 v0, 0x4000, v104
	v_ashrrev_i32_e32 v1, 31, v104
	v_readlane_b32 s0, v253, 42
	v_ashrrev_i32_e32 v172, 13, v0
	v_add_u32_e32 v0, 0xffffc000, v104
	v_cndmask_b32_e32 v105, 0, v1, vcc
	v_mov_b32_e32 v2, s0
	v_mov_b32_e32 v3, s89
	v_readlane_b32 s0, v255, 17
	v_cndmask_b32_e32 v0, v0, v104, vcc
	v_mov_b32_e32 v1, v105
	v_cndmask_b32_e32 v3, v2, v3, vcc
	v_mov_b32_e32 v2, s0
	v_mov_b32_e32 v4, s88
	v_cndmask_b32_e32 v2, v2, v4, vcc
	v_lshlrev_b64 v[0:1], 12, v[0:1]
	v_lshl_add_u64 v[120:121], v[2:3], 0, v[0:1]
	v_add_u32_e32 v0, s10, v172
	v_mul_hi_i32_i24_e32 v33, 0x6000, v0
	v_mul_i32_i24_e32 v32, 0x6000, v0
	v_lshl_add_u64 v[0:1], v[120:121], 0, v[192:193]
	s_movk_i32 s12, 0x1000
	v_add_co_u32_e32 v2, vcc, s12, v0
	s_movk_i32 s13, 0x2000
	s_nop 0
	v_addc_co_u32_e32 v3, vcc, 0, v1, vcc
	v_add_co_u32_e32 v4, vcc, s13, v0
	global_load_dwordx4 v[92:95], v[0:1], off nt
	global_load_dwordx4 v[88:91], v[0:1], off offset:1024 nt
	global_load_dwordx4 v[84:87], v[0:1], off offset:2048 nt
	global_load_dwordx4 v[80:83], v[0:1], off offset:3072 nt
	v_addc_co_u32_e32 v5, vcc, 0, v1, vcc
	v_add_co_u32_e32 v0, vcc, s73, v0
	global_load_dwordx4 v[76:79], v[4:5], off offset:-4096 nt
	global_load_dwordx4 v[72:75], v[2:3], off offset:1024 nt
	global_load_dwordx4 v[68:71], v[2:3], off offset:2048 nt
	global_load_dwordx4 v[64:67], v[2:3], off offset:3072 nt
	global_load_dwordx4 v[28:31], v[4:5], off nt
	global_load_dwordx4 v[24:27], v[4:5], off offset:1024 nt
	global_load_dwordx4 v[20:23], v[4:5], off offset:2048 nt
	global_load_dwordx4 v[16:19], v[4:5], off offset:3072 nt
	v_addc_co_u32_e32 v1, vcc, 0, v1, vcc
	global_load_dwordx4 v[12:15], v[0:1], off nt
	global_load_dwordx4 v[8:11], v[0:1], off offset:1024 nt
	global_load_dwordx4 v[4:7], v[0:1], off offset:2048 nt
	s_nop 0
	global_load_dwordx4 v[0:3], v[0:1], off offset:3072 nt
	v_add_u32_e32 v34, 1, v104
	v_ashrrev_i32_e32 v35, 31, v34
	v_lshlrev_b64 v[116:117], 11, v[34:35]
	v_add_u32_e32 v34, 2, v104
	v_ashrrev_i32_e32 v35, 31, v34
	v_lshlrev_b64 v[114:115], 11, v[34:35]
	v_add_u32_e32 v34, 3, v104
	v_ashrrev_i32_e32 v35, 31, v34
	v_cmp_lt_i32_e32 vcc, v211, v210
	v_lshlrev_b64 v[112:113], 11, v[34:35]
	v_lshl_add_u64 v[32:33], s[90:91], 0, v[32:33]
	v_cndmask_b32_e32 v34, v209, v211, vcc
	v_cmp_lt_i32_e32 vcc, v212, v210
	v_lshlrev_b32_e32 v107, 2, v34
	v_lshl_add_u64 v[36:37], v[32:33], 0, v[192:193]
	v_cndmask_b32_e32 v34, v209, v212, vcc
	v_cmp_lt_i32_e32 vcc, v206, v210
	v_lshlrev_b32_e32 v109, 2, v34
	s_mov_b64 s[0:1], 0x345d000
	v_cndmask_b32_e32 v34, v209, v206, vcc
	v_cmp_lt_i32_e32 vcc, v213, v210
	v_lshlrev_b32_e32 v111, 2, v34
	v_lshl_add_u64 v[62:63], v[36:37], 0, s[0:1]
	v_cndmask_b32_e32 v34, v209, v213, vcc
	v_cmp_lt_i32_e32 vcc, v216, v210
	v_lshlrev_b32_e32 v169, 2, v34
	s_mov_b32 s0, 0x345d000
	v_cndmask_b32_e32 v34, v209, v216, vcc
	v_cmp_lt_i32_e32 vcc, v217, v210
	v_lshlrev_b32_e32 v170, 2, v34
	v_lshlrev_b64 v[118:119], 11, v[104:105]
	v_cndmask_b32_e32 v34, v209, v217, vcc
	v_add_co_u32_e32 v36, vcc, s0, v36
	v_lshl_add_u64 v[60:61], v[96:97], 0, v[118:119]
	s_nop 0
	v_addc_co_u32_e32 v37, vcc, 0, v37, vcc
	v_lshlrev_b32_e32 v171, 2, v34
	global_load_dwordx4 v[32:35], v[98:99], off
	v_lshl_add_u64 v[140:141], v[96:97], 0, v[116:117]
	global_load_dwordx4 v[36:39], v[36:37], off
	s_nop 0
	global_load_dwordx4 v[40:43], v[98:99], off offset:1024
	global_load_dwordx4 v[44:47], v[62:63], off offset:1024
	global_load_dwordx4 v[48:51], v[98:99], off offset:2048
	global_load_dwordx4 v[52:55], v[62:63], off offset:2048
	s_mov_b32 s0, 0x358637bd
	s_mov_b32 s16, 0x3a800000
	s_mov_b32 s14, 0x800000
	v_lshl_add_u64 v[134:135], v[96:97], 0, v[114:115]
	v_lshl_add_u64 v[124:125], v[96:97], 0, v[112:113]
	s_waitcnt vmcnt(21)
	v_mov_b32_e32 v138, v92
	s_waitcnt vmcnt(17)
	v_mov_b32_e32 v136, v76
	s_waitcnt vmcnt(16)
	v_mov_b32_e32 v142, v72
	v_mov_b32_e32 v143, v74
	v_mov_b32_e32 v74, v73
	v_mov_b32_e32 v137, v78
	s_waitcnt vmcnt(12)
	v_mov_b32_e32 v72, v24
	v_mov_b32_e32 v73, v26
	v_mov_b32_e32 v26, v25
	v_mov_b32_e32 v24, v68
	v_mov_b32_e32 v25, v70
	v_mov_b32_e32 v70, v69
	s_waitcnt vmcnt(7)
	v_mov_b32_e32 v68, v4
	v_mov_b32_e32 v69, v6
	v_mov_b32_e32 v6, v5
	global_load_dwordx4 v[56:59], v[98:99], off offset:3072
	global_load_dwordx2 v[4:5], v[60:61], off offset:1536 nt
	global_load_dwordx2 v[180:181], v[60:61], off offset:1024 nt
	global_load_dwordx2 v[182:183], v[60:61], off offset:512 nt
	global_load_dwordx2 v[184:185], v[60:61], off nt
	global_load_dwordx2 v[186:187], v[140:141], off offset:1536 nt
	global_load_dwordx2 v[188:189], v[140:141], off offset:1024 nt
	global_load_dwordx2 v[190:191], v[140:141], off offset:512 nt
	global_load_dwordx2 v[224:225], v[140:141], off nt
	global_load_dwordx2 v[232:233], v[134:135], off offset:1536 nt
	global_load_dwordx2 v[234:235], v[134:135], off offset:1024 nt
	global_load_dwordx2 v[236:237], v[134:135], off offset:512 nt
	global_load_dwordx2 v[238:239], v[134:135], off nt
	global_load_dwordx2 v[240:241], v[124:125], off offset:1536 nt
	global_load_dwordx2 v[242:243], v[124:125], off offset:1024 nt
	global_load_dwordx2 v[248:249], v[124:125], off offset:512 nt
	global_load_dwordx2 v[250:251], v[124:125], off nt
	v_mov_b32_e32 v78, v77
	v_mov_b32_e32 v144, v84
	v_mov_b32_e32 v145, v86
	v_mov_b32_e32 v86, v85
	v_mov_b32_e32 v84, v20
	v_mov_b32_e32 v85, v22
	v_mov_b32_e32 v22, v21
	v_mov_b32_e32 v139, v94
	v_mov_b32_e32 v94, v93
	s_waitcnt vmcnt(22)
	v_mov_b32_e32 v130, v32
	v_mov_b32_e32 v131, v34
	s_waitcnt vmcnt(21)
	v_mov_b32_e32 v122, v36
	s_waitcnt vmcnt(19)
	v_mov_b32_e32 v76, v44
	v_mov_b32_e32 v77, v46
	v_mov_b32_e32 v46, v45
	v_mov_b32_e32 v44, v8
	v_mov_b32_e32 v45, v10
	v_mov_b32_e32 v10, v9
	s_waitcnt vmcnt(17)
	v_mov_b32_e32 v8, v52
	v_mov_b32_e32 v9, v54
	v_mov_b32_e32 v54, v53
	v_mov_b32_e32 v123, v38
	v_mov_b32_e32 v38, v37
	v_mov_b32_e32 v36, v28
	v_mov_b32_e32 v37, v30
	v_mov_b32_e32 v30, v29
	v_mov_b32_e32 v28, v12
	v_mov_b32_e32 v29, v14
	v_mov_b32_e32 v14, v13
	v_mov_b32_e32 v12, v88
	v_mov_b32_e32 v13, v90
	v_mov_b32_e32 v90, v89
	v_mov_b32_e32 v34, v33
	v_mov_b32_e32 v32, v80
	v_mov_b32_e32 v33, v82
	v_mov_b32_e32 v82, v81
	s_waitcnt vmcnt(15)
	v_and_b32_e32 v21, 0xffff0000, v5
	v_and_b32_e32 v20, 0xffff0000, v4
	v_lshlrev_b32_e32 v52, 16, v4
	v_lshlrev_b32_e32 v53, 16, v5
	v_mov_b32_e32 v93, v52
	v_mov_b32_e32 v127, v53
	v_mov_b32_e32 v89, v21
	s_waitcnt vmcnt(14)
	v_mov_b32_e32 v4, v180
	v_mov_b32_e32 v5, v181
	v_and_b32_e32 v146, 0xffff0000, v4
	v_and_b32_e32 v147, 0xffff0000, v5
	v_lshlrev_b32_e32 v148, 16, v4
	v_lshlrev_b32_e32 v149, 16, v5
	v_mov_b32_e32 v4, v146
	v_mov_b32_e32 v5, v20
	v_pk_mul_f32 v[4:5], v[4:5], v[4:5]
	v_mov_b32_e32 v92, v148
	v_mov_b32_e32 v126, v149
	v_pk_fma_f32 v[4:5], v[92:93], v[92:93], v[4:5]
	v_mov_b32_e32 v88, v147
	v_pk_fma_f32 v[4:5], v[126:127], v[126:127], v[4:5]
	s_nop 0
	v_pk_fma_f32 v[88:89], v[88:89], v[88:89], v[4:5]
	s_waitcnt vmcnt(13)
	v_mov_b32_e32 v4, v182
	v_mov_b32_e32 v5, v183
	v_and_b32_e32 v151, 0xffff0000, v5
	v_and_b32_e32 v150, 0xffff0000, v4
	v_lshlrev_b32_e32 v152, 16, v4
	v_lshlrev_b32_e32 v153, 16, v5
	v_mov_b32_e32 v127, v152
	v_mov_b32_e32 v129, v153
	v_mov_b32_e32 v61, v151
	s_waitcnt vmcnt(12)
	v_mov_b32_e32 v4, v184
	v_mov_b32_e32 v5, v185
	v_and_b32_e32 v92, 0xffff0000, v4
	v_and_b32_e32 v93, 0xffff0000, v5
	v_lshlrev_b32_e32 v154, 16, v4
	v_lshlrev_b32_e32 v155, 16, v5
	v_mov_b32_e32 v4, v92
	v_mov_b32_e32 v5, v150
	v_pk_mul_f32 v[4:5], v[4:5], v[4:5]
	v_mov_b32_e32 v126, v154
	v_mov_b32_e32 v128, v155
	v_pk_fma_f32 v[4:5], v[126:127], v[126:127], v[4:5]
	v_mov_b32_e32 v60, v93
	v_pk_fma_f32 v[4:5], v[128:129], v[128:129], v[4:5]
	v_mov_b32_e32 v128, v40
	v_mov_b32_e32 v129, v42
	v_mov_b32_e32 v42, v41
	v_pk_fma_f32 v[156:157], v[60:61], v[60:61], v[4:5]
	global_load_dwordx4 v[60:63], v[62:63], off offset:3072
	v_mov_b32_e32 v126, v48
	v_mov_b32_e32 v127, v50
	v_mov_b32_e32 v50, v49
	v_mov_b32_e32 v4, v56
	v_mov_b32_e32 v5, v58
	v_mov_b32_e32 v58, v57
	s_waitcnt vmcnt(12)
	v_mov_b32_e32 v40, v186
	v_mov_b32_e32 v41, v187
	v_and_b32_e32 v159, 0xffff0000, v41
	v_and_b32_e32 v158, 0xffff0000, v40
	v_lshlrev_b32_e32 v160, 16, v40
	v_lshlrev_b32_e32 v161, 16, v41
	s_waitcnt vmcnt(0)
	v_mov_b32_e32 v132, v60
	v_mov_b32_e32 v133, v62
	v_mov_b32_e32 v62, v61
	v_mov_b32_e32 v61, v160
	v_mov_b32_e32 v81, v161
	v_mov_b32_e32 v57, v159
	s_waitcnt vmcnt(0)
	v_mov_b32_e32 v40, v188
	v_mov_b32_e32 v41, v189
	v_and_b32_e32 v48, 0xffff0000, v40
	v_and_b32_e32 v49, 0xffff0000, v41
	v_lshlrev_b32_e32 v162, 16, v40
	v_lshlrev_b32_e32 v163, 16, v41
	v_mov_b32_e32 v40, v48
	v_mov_b32_e32 v41, v158
	v_pk_mul_f32 v[40:41], v[40:41], v[40:41]
	v_mov_b32_e32 v60, v162
	v_mov_b32_e32 v80, v163
	v_pk_fma_f32 v[40:41], v[60:61], v[60:61], v[40:41]
	v_mov_b32_e32 v56, v49
	v_pk_fma_f32 v[40:41], v[80:81], v[80:81], v[40:41]
	s_nop 0
	v_pk_fma_f32 v[40:41], v[56:57], v[56:57], v[40:41]
	s_waitcnt vmcnt(0)
	v_mov_b32_e32 v56, v190
	v_mov_b32_e32 v57, v191
	v_and_b32_e32 v165, 0xffff0000, v57
	v_and_b32_e32 v164, 0xffff0000, v56
	v_lshlrev_b32_e32 v166, 16, v56
	v_lshlrev_b32_e32 v167, 16, v57
	v_mov_b32_e32 v81, v166
	v_mov_b32_e32 v141, v167
	v_mov_b32_e32 v61, v165
	s_waitcnt vmcnt(0)
	v_mov_b32_e32 v56, v224
	v_mov_b32_e32 v57, v225
	v_and_b32_e32 v174, 0xffff0000, v56
	v_and_b32_e32 v175, 0xffff0000, v57
	v_lshlrev_b32_e32 v176, 16, v56
	v_lshlrev_b32_e32 v177, 16, v57
	v_mov_b32_e32 v56, v174
	v_mov_b32_e32 v57, v164
	v_pk_mul_f32 v[56:57], v[56:57], v[56:57]
	v_mov_b32_e32 v80, v176
	v_mov_b32_e32 v140, v177
	v_pk_fma_f32 v[56:57], v[80:81], v[80:81], v[56:57]
	v_mov_b32_e32 v60, v175
	v_pk_fma_f32 v[56:57], v[140:141], v[140:141], v[56:57]
	v_mov_b64_e32 v[140:141], s[0:1]
	v_pk_fma_f32 v[56:57], v[60:61], v[60:61], v[56:57]
	v_mov_b32_e32 v61, v156
	v_mov_b32_e32 v60, v56
	v_mov_b32_e32 v156, v57
	v_pk_add_f32 v[56:57], v[60:61], v[156:157]
	v_mov_b32_e32 v60, v40
	v_mov_b32_e32 v61, v88
	v_pk_add_f32 v[56:57], v[56:57], v[60:61]
	v_mov_b32_e32 v88, v41
	v_pk_add_f32 v[40:41], v[56:57], v[88:89]
	ds_bpermute_b32 v57, v107, v41
	ds_bpermute_b32 v56, v107, v40
	s_waitcnt lgkmcnt(0)
	v_pk_add_f32 v[40:41], v[40:41], v[56:57]
	ds_bpermute_b32 v57, v109, v41
	ds_bpermute_b32 v56, v109, v40
	s_waitcnt lgkmcnt(0)
	v_pk_add_f32 v[40:41], v[40:41], v[56:57]
	ds_bpermute_b32 v57, v111, v41
	ds_bpermute_b32 v56, v111, v40
	s_waitcnt lgkmcnt(0)
	v_pk_add_f32 v[40:41], v[40:41], v[56:57]
	ds_bpermute_b32 v57, v169, v41
	ds_bpermute_b32 v56, v169, v40
	s_waitcnt lgkmcnt(0)
	v_pk_add_f32 v[40:41], v[40:41], v[56:57]
	ds_bpermute_b32 v57, v170, v41
	ds_bpermute_b32 v56, v170, v40
	s_waitcnt lgkmcnt(0)
	v_pk_add_f32 v[40:41], v[40:41], v[56:57]
	ds_bpermute_b32 v57, v171, v41
	ds_bpermute_b32 v56, v171, v40
	s_waitcnt lgkmcnt(0)
	v_pk_add_f32 v[40:41], v[40:41], v[56:57]
	s_nop 0
	v_pk_fma_f32 v[156:157], v[40:41], s[16:17], v[140:141] op_sel_hi:[1,0,0]
	s_nop 0
	v_mul_f32_e32 v40, 0x4b800000, v157
	v_cmp_gt_f32_e64 s[0:1], s14, v157
	v_cmp_gt_f32_e32 vcc, s14, v156
	s_nop 0
	v_cndmask_b32_e64 v40, v157, v40, s[0:1]
	v_rsq_f32_e32 v40, v40
	s_nop 0
	v_mul_f32_e32 v41, 0x45800000, v40
	v_cndmask_b32_e64 v178, v40, v41, s[0:1]
	v_pk_mul_f32 v[40:41], v[178:179], v[154:155] op_sel_hi:[0,1]
	v_pk_mul_f32 v[40:41], v[40:41], v[130:131]
	v_pk_mul_f32 v[56:57], v[178:179], v[92:93] op_sel_hi:[0,1]
	v_pk_fma_f32 v[92:93], v[40:41], v[122:123], v[138:139]
	v_pk_mul_f32 v[40:41], v[178:179], v[152:153] op_sel_hi:[0,1]
	v_pk_mul_f32 v[56:57], v[56:57], v[34:35]
	v_pk_mul_f32 v[40:41], v[40:41], v[128:129]
	v_pk_fma_f32 v[88:89], v[56:57], v[38:39], v[94:95]
	v_pk_mul_f32 v[56:57], v[178:179], v[150:151] op_sel_hi:[0,1]
	v_pk_fma_f32 v[80:81], v[40:41], v[76:77], v[12:13]
	v_pk_mul_f32 v[12:13], v[178:179], v[148:149] op_sel_hi:[0,1]
	v_pk_mul_f32 v[56:57], v[56:57], v[42:43]
	v_pk_mul_f32 v[12:13], v[12:13], v[126:127]
	v_pk_fma_f32 v[60:61], v[56:57], v[46:47], v[90:91]
	v_pk_fma_f32 v[56:57], v[12:13], v[8:9], v[144:145]
	v_pk_mul_f32 v[12:13], v[178:179], v[52:53] op_sel_hi:[0,1]
	v_pk_mul_f32 v[20:21], v[178:179], v[20:21] op_sel_hi:[0,1]
	v_pk_mul_f32 v[12:13], v[12:13], v[4:5]
	v_pk_mul_f32 v[20:21], v[20:21], v[58:59]
	v_pk_fma_f32 v[32:33], v[12:13], v[132:133], v[32:33]
	v_pk_fma_f32 v[12:13], v[20:21], v[62:63], v[82:83]
	v_mul_f32_e32 v20, 0x4b800000, v156
	v_cndmask_b32_e32 v20, v156, v20, vcc
	v_rsq_f32_e32 v20, v20
	v_pk_mul_f32 v[40:41], v[178:179], v[146:147] op_sel_hi:[0,1]
	v_pk_mul_f32 v[40:41], v[40:41], v[50:51]
	v_mul_f32_e32 v21, 0x45800000, v20
	v_cndmask_b32_e32 v20, v20, v21, vcc
	v_pk_mul_f32 v[48:49], v[20:21], v[48:49] op_sel_hi:[0,1]
	v_pk_mul_f32 v[48:49], v[48:49], v[50:51]
	v_pk_mul_f32 v[82:83], v[20:21], v[174:175] op_sel_hi:[0,1]
	v_pk_fma_f32 v[48:49], v[48:49], v[54:55], v[70:71]
	v_mov_b32_e32 v70, v64
	v_mov_b32_e32 v71, v66
	v_mov_b32_e32 v66, v65
	v_pk_mul_f32 v[82:83], v[82:83], v[34:35]
	v_pk_mul_f32 v[52:53], v[20:21], v[176:177] op_sel_hi:[0,1]
	v_pk_fma_f32 v[82:83], v[82:83], v[38:39], v[78:79]
	v_pk_mul_f32 v[78:79], v[20:21], v[164:165] op_sel_hi:[0,1]
	v_pk_mul_f32 v[90:91], v[78:79], v[42:43]
	v_pk_mul_f32 v[52:53], v[52:53], v[130:131]
	v_pk_fma_f32 v[74:75], v[90:91], v[46:47], v[74:75]
	v_pk_fma_f32 v[40:41], v[40:41], v[54:55], v[86:87]
	v_pk_fma_f32 v[86:87], v[52:53], v[122:123], v[136:137]
	v_pk_mul_f32 v[52:53], v[20:21], v[166:167] op_sel_hi:[0,1]
	v_pk_mul_f32 v[52:53], v[52:53], v[128:129]
	s_waitcnt vmcnt(0)
	v_mov_b32_e32 v64, v232
	v_mov_b32_e32 v65, v233
	v_and_b32_e32 v91, 0xffff0000, v65
	v_and_b32_e32 v90, 0xffff0000, v64
	v_lshlrev_b32_e32 v94, 16, v64
	v_lshlrev_b32_e32 v95, 16, v65
	v_pk_fma_f32 v[78:79], v[52:53], v[76:77], v[142:143]
	v_pk_mul_f32 v[52:53], v[20:21], v[162:163] op_sel_hi:[0,1]
	v_pk_mul_f32 v[52:53], v[52:53], v[126:127]
	v_mov_b32_e32 v143, v95
	v_pk_fma_f32 v[52:53], v[52:53], v[8:9], v[24:25]
	v_pk_mul_f32 v[24:25], v[20:21], v[160:161] op_sel_hi:[0,1]
	v_pk_mul_f32 v[24:25], v[24:25], v[4:5]
	v_pk_mul_f32 v[20:21], v[20:21], v[158:159] op_sel_hi:[0,1]
	v_pk_fma_f32 v[24:25], v[24:25], v[132:133], v[70:71]
	v_mov_b32_e32 v71, v94
	v_pk_mul_f32 v[20:21], v[20:21], v[58:59]
	s_waitcnt vmcnt(0)
	v_mov_b32_e32 v64, v234
	v_mov_b32_e32 v65, v235
	v_and_b32_e32 v136, 0xffff0000, v64
	v_and_b32_e32 v137, 0xffff0000, v65
	v_lshlrev_b32_e32 v138, 16, v64
	v_lshlrev_b32_e32 v139, 16, v65
	v_mov_b32_e32 v64, v136
	v_mov_b32_e32 v65, v90
	v_pk_mul_f32 v[64:65], v[64:65], v[64:65]
	v_mov_b32_e32 v70, v138
	v_pk_fma_f32 v[64:65], v[70:71], v[70:71], v[64:65]
	v_mov_b32_e32 v142, v139
	v_pk_fma_f32 v[20:21], v[20:21], v[62:63], v[66:67]
	v_mov_b32_e32 v66, v137
	v_mov_b32_e32 v67, v91
	v_pk_fma_f32 v[64:65], v[142:143], v[142:143], v[64:65]
	s_waitcnt vmcnt(0)
	v_mov_b32_e32 v70, v236
	v_mov_b32_e32 v71, v237
	v_lshlrev_b32_e32 v142, 16, v70
	v_pk_fma_f32 v[66:67], v[66:67], v[66:67], v[64:65]
	v_and_b32_e32 v64, 0xffff0000, v70
	s_waitcnt vmcnt(0)
	v_mov_b32_e32 v134, v238
	v_mov_b32_e32 v135, v239
	v_and_b32_e32 v70, 0xffff0000, v134
	v_and_b32_e32 v65, 0xffff0000, v71
	v_lshlrev_b32_e32 v143, 16, v71
	v_and_b32_e32 v71, 0xffff0000, v135
	v_lshlrev_b32_e32 v144, 16, v134
	v_lshlrev_b32_e32 v145, 16, v135
	v_mov_b32_e32 v134, v70
	v_mov_b32_e32 v135, v64
	v_pk_mul_f32 v[134:135], v[134:135], v[134:135]
	v_mov_b32_e32 v148, v144
	v_mov_b32_e32 v149, v142
	v_mov_b32_e32 v150, v145
	v_mov_b32_e32 v151, v143
	v_pk_fma_f32 v[134:135], v[148:149], v[148:149], v[134:135]
	v_mov_b32_e32 v146, v71
	v_mov_b32_e32 v147, v65
	v_pk_fma_f32 v[134:135], v[150:151], v[150:151], v[134:135]
	s_nop 0
	v_pk_fma_f32 v[154:155], v[146:147], v[146:147], v[134:135]
	v_mov_b32_e32 v134, v16
	v_mov_b32_e32 v135, v18
	v_mov_b32_e32 v18, v17
	s_waitcnt vmcnt(0)
	v_mov_b32_e32 v16, v240
	v_mov_b32_e32 v17, v241
	v_and_b32_e32 v147, 0xffff0000, v17
	v_and_b32_e32 v146, 0xffff0000, v16
	v_lshlrev_b32_e32 v148, 16, v16
	v_lshlrev_b32_e32 v149, 16, v17
	v_mov_b32_e32 v159, v148
	v_mov_b32_e32 v161, v149
	v_mov_b32_e32 v157, v147
	s_waitcnt vmcnt(0)
	v_mov_b32_e32 v16, v242
	v_mov_b32_e32 v17, v243
	v_and_b32_e32 v150, 0xffff0000, v16
	v_and_b32_e32 v151, 0xffff0000, v17
	v_lshlrev_b32_e32 v152, 16, v16
	v_lshlrev_b32_e32 v153, 16, v17
	v_mov_b32_e32 v16, v150
	v_mov_b32_e32 v17, v146
	v_pk_mul_f32 v[16:17], v[16:17], v[16:17]
	v_mov_b32_e32 v158, v152
	v_pk_fma_f32 v[16:17], v[158:159], v[158:159], v[16:17]
	v_mov_b32_e32 v160, v153
	v_mov_b32_e32 v156, v151
	v_pk_fma_f32 v[16:17], v[160:161], v[160:161], v[16:17]
	s_waitcnt vmcnt(0)
	v_mov_b32_e32 v158, v248
	v_mov_b32_e32 v159, v249
	v_mov_b32_e32 v124, v250
	v_mov_b32_e32 v125, v251
	v_and_b32_e32 v160, 0xffff0000, v124
	v_pk_fma_f32 v[16:17], v[156:157], v[156:157], v[16:17]
	v_and_b32_e32 v156, 0xffff0000, v158
	v_lshlrev_b32_e32 v158, 16, v158
	v_lshlrev_b32_e32 v124, 16, v124
	v_mov_b32_e32 v162, v160
	v_mov_b32_e32 v163, v156
	v_and_b32_e32 v157, 0xffff0000, v159
	v_lshlrev_b32_e32 v159, 16, v159
	v_and_b32_e32 v161, 0xffff0000, v125
	v_lshlrev_b32_e32 v125, 16, v125
	v_pk_mul_f32 v[162:163], v[162:163], v[162:163]
	v_mov_b32_e32 v166, v124
	v_mov_b32_e32 v167, v158
	v_mov_b32_e32 v174, v125
	v_mov_b32_e32 v175, v159
	v_pk_fma_f32 v[162:163], v[166:167], v[166:167], v[162:163]
	v_mov_b32_e32 v164, v161
	v_mov_b32_e32 v165, v157
	v_pk_fma_f32 v[162:163], v[174:175], v[174:175], v[162:163]
	s_nop 0
	v_pk_fma_f32 v[162:163], v[164:165], v[164:165], v[162:163]
	v_mov_b32_e32 v165, v154
	v_mov_b32_e32 v164, v162
	v_mov_b32_e32 v154, v163
	v_pk_add_f32 v[154:155], v[164:165], v[154:155]
	v_mov_b32_e32 v162, v16
	v_mov_b32_e32 v163, v66
	v_pk_add_f32 v[154:155], v[154:155], v[162:163]
	v_mov_b32_e32 v66, v17
	v_pk_add_f32 v[16:17], v[154:155], v[66:67]
	ds_bpermute_b32 v67, v107, v17
	ds_bpermute_b32 v66, v107, v16
	s_waitcnt lgkmcnt(0)
	v_pk_add_f32 v[16:17], v[16:17], v[66:67]
	ds_bpermute_b32 v67, v109, v17
	ds_bpermute_b32 v66, v109, v16
	s_waitcnt lgkmcnt(0)
	v_pk_add_f32 v[16:17], v[16:17], v[66:67]
	ds_bpermute_b32 v67, v111, v17
	ds_bpermute_b32 v66, v111, v16
	s_waitcnt lgkmcnt(0)
	v_pk_add_f32 v[16:17], v[16:17], v[66:67]
	ds_bpermute_b32 v67, v169, v17
	ds_bpermute_b32 v66, v169, v16
	s_waitcnt lgkmcnt(0)
	v_pk_add_f32 v[16:17], v[16:17], v[66:67]
	ds_bpermute_b32 v67, v170, v17
	ds_bpermute_b32 v66, v170, v16
	s_waitcnt lgkmcnt(0)
	v_pk_add_f32 v[16:17], v[16:17], v[66:67]
	ds_bpermute_b32 v67, v171, v17
	ds_bpermute_b32 v66, v171, v16
	s_waitcnt lgkmcnt(0)
	v_pk_add_f32 v[16:17], v[16:17], v[66:67]
	s_nop 0
	v_pk_fma_f32 v[140:141], v[16:17], s[16:17], v[140:141] op_sel_hi:[1,0,0]
	s_nop 0
	v_mul_f32_e32 v16, 0x4b800000, v141
	v_cmp_gt_f32_e64 s[0:1], s14, v141
	v_cmp_gt_f32_e32 vcc, s14, v140
	s_nop 0
	v_cndmask_b32_e64 v16, v141, v16, s[0:1]
	v_rsq_f32_e32 v16, v16
	s_nop 0
	v_mul_f32_e32 v17, 0x45800000, v16
	v_cndmask_b32_e64 v16, v16, v17, s[0:1]
	v_pk_mul_f32 v[66:67], v[16:17], v[144:145] op_sel_hi:[0,1]
	v_pk_mul_f32 v[70:71], v[16:17], v[70:71] op_sel_hi:[0,1]
	v_pk_mul_f32 v[66:67], v[130:131], v[66:67]
	v_pk_mul_f32 v[144:145], v[34:35], v[70:71]
	v_pk_fma_f32 v[70:71], v[122:123], v[66:67], v[36:37]
	v_pk_fma_f32 v[66:67], v[144:145], v[38:39], v[30:31]
	v_pk_mul_f32 v[30:31], v[16:17], v[142:143] op_sel_hi:[0,1]
	v_pk_mul_f32 v[36:37], v[16:17], v[64:65] op_sel_hi:[0,1]
	v_pk_mul_f32 v[30:31], v[30:31], v[128:129]
	v_pk_mul_f32 v[36:37], v[36:37], v[42:43]
	v_pk_fma_f32 v[64:65], v[30:31], v[76:77], v[72:73]
	v_pk_fma_f32 v[36:37], v[36:37], v[46:47], v[26:27]
	v_pk_mul_f32 v[26:27], v[16:17], v[138:139] op_sel_hi:[0,1]
	v_pk_mul_f32 v[30:31], v[16:17], v[136:137] op_sel_hi:[0,1]
	v_pk_mul_f32 v[26:27], v[26:27], v[126:127]
	v_pk_mul_f32 v[72:73], v[30:31], v[50:51]
	v_pk_fma_f32 v[30:31], v[26:27], v[8:9], v[84:85]
	v_pk_fma_f32 v[26:27], v[72:73], v[54:55], v[22:23]
	v_pk_mul_f32 v[22:23], v[16:17], v[94:95] op_sel_hi:[0,1]
	v_pk_mul_f32 v[16:17], v[16:17], v[90:91] op_sel_hi:[0,1]
	v_pk_mul_f32 v[16:17], v[16:17], v[58:59]
	v_pk_mul_f32 v[22:23], v[22:23], v[4:5]
	v_pk_fma_f32 v[16:17], v[16:17], v[62:63], v[18:19]
	v_mul_f32_e32 v18, 0x4b800000, v140
	v_cndmask_b32_e32 v18, v140, v18, vcc
	v_rsq_f32_e32 v18, v18
	v_pk_fma_f32 v[22:23], v[22:23], v[132:133], v[134:135]
	v_mul_f32_e32 v19, 0x45800000, v18
	v_cndmask_b32_e32 v18, v18, v19, vcc
	v_pk_mul_f32 v[72:73], v[18:19], v[124:125] op_sel_hi:[0,1]
	v_pk_mul_f32 v[84:85], v[18:19], v[160:161] op_sel_hi:[0,1]
	v_pk_mul_f32 v[72:73], v[130:131], v[72:73]
	v_pk_mul_f32 v[34:35], v[34:35], v[84:85]
	v_pk_fma_f32 v[84:85], v[122:123], v[72:73], v[28:29]
	v_pk_fma_f32 v[72:73], v[38:39], v[34:35], v[14:15]
	v_pk_mul_f32 v[14:15], v[18:19], v[158:159] op_sel_hi:[0,1]
	v_pk_mul_f32 v[28:29], v[18:19], v[156:157] op_sel_hi:[0,1]
	v_pk_mul_f32 v[14:15], v[128:129], v[14:15]
	v_pk_mul_f32 v[28:29], v[42:43], v[28:29]
	v_pk_fma_f32 v[42:43], v[14:15], v[76:77], v[44:45]
	v_pk_fma_f32 v[38:39], v[28:29], v[46:47], v[10:11]
	v_pk_mul_f32 v[10:11], v[18:19], v[152:153] op_sel_hi:[0,1]
	v_pk_mul_f32 v[14:15], v[18:19], v[150:151] op_sel_hi:[0,1]
	v_pk_mul_f32 v[10:11], v[10:11], v[126:127]
	v_pk_mul_f32 v[14:15], v[14:15], v[50:51]
	v_pk_fma_f32 v[34:35], v[10:11], v[8:9], v[68:69]
	v_pk_fma_f32 v[28:29], v[14:15], v[54:55], v[6:7]
	v_pk_mul_f32 v[6:7], v[18:19], v[148:149] op_sel_hi:[0,1]
	v_mov_b32_e32 v8, v0
	v_mov_b32_e32 v9, v2
	v_mov_b32_e32 v2, v1
	v_lshlrev_b64 v[0:1], 12, v[104:105]
	v_pk_mul_f32 v[4:5], v[6:7], v[4:5]
	v_pk_mul_f32 v[6:7], v[18:19], v[146:147] op_sel_hi:[0,1]
	v_lshl_add_u64 v[0:1], s[88:89], 0, v[0:1]
	v_pk_mul_f32 v[6:7], v[6:7], v[58:59]
	v_cndmask_b32_e64 v1, v121, v1, s[2:3]
	v_cndmask_b32_e64 v0, v120, v0, s[2:3]
	v_pk_fma_f32 v[14:15], v[4:5], v[132:133], v[8:9]
	v_pk_fma_f32 v[18:19], v[6:7], v[62:63], v[2:3]
	v_lshl_add_u64 v[4:5], v[0:1], 0, v[192:193]
	v_mov_b32_e32 v0, v92
	v_mov_b32_e32 v1, v88
	v_mov_b32_e32 v2, v93
	v_mov_b32_e32 v3, v89
	global_store_dwordx4 v[4:5], v[0:3], off nt
	v_add_co_u32_e32 v6, vcc, s12, v4
	s_nop 0
	v_mov_b32_e32 v0, v80
	v_mov_b32_e32 v1, v60
	v_mov_b32_e32 v2, v81
	v_mov_b32_e32 v3, v61
	global_store_dwordx4 v[4:5], v[0:3], off offset:1024 nt
	v_addc_co_u32_e32 v7, vcc, 0, v5, vcc
	s_nop 0
	v_mov_b32_e32 v0, v56
	v_mov_b32_e32 v1, v40
	v_mov_b32_e32 v2, v57
	v_mov_b32_e32 v3, v41
	global_store_dwordx4 v[4:5], v[0:3], off offset:2048 nt
	v_add_co_u32_e32 v8, vcc, s13, v4
	s_nop 0
	v_mov_b32_e32 v0, v32
	v_mov_b32_e32 v1, v12
	v_mov_b32_e32 v2, v33
	v_mov_b32_e32 v3, v13
	global_store_dwordx4 v[4:5], v[0:3], off offset:3072 nt
	v_addc_co_u32_e32 v9, vcc, 0, v5, vcc
	s_nop 0
	v_mov_b32_e32 v0, v86
	v_mov_b32_e32 v1, v82
	v_mov_b32_e32 v2, v87
	v_mov_b32_e32 v3, v83
	global_store_dwordx4 v[8:9], v[0:3], off offset:-4096 nt
	v_add_co_u32_e32 v4, vcc, s73, v4
	s_nop 0
	v_mov_b32_e32 v0, v78
	v_mov_b32_e32 v1, v74
	v_mov_b32_e32 v2, v79
	v_mov_b32_e32 v3, v75
	global_store_dwordx4 v[6:7], v[0:3], off offset:1024 nt
	v_addc_co_u32_e32 v5, vcc, 0, v5, vcc
	s_nop 0
	v_mov_b32_e32 v0, v52
	v_mov_b32_e32 v1, v48
	v_mov_b32_e32 v2, v53
	v_mov_b32_e32 v3, v49
	global_store_dwordx4 v[6:7], v[0:3], off offset:2048 nt
	s_andn2_b64 vcc, exec, s[4:5]
	s_nop 0
	v_mov_b32_e32 v0, v24
	v_mov_b32_e32 v1, v20
	v_mov_b32_e32 v2, v25
	v_mov_b32_e32 v3, v21
	global_store_dwordx4 v[6:7], v[0:3], off offset:3072 nt
	s_nop 1
	v_mov_b32_e32 v0, v70
	v_mov_b32_e32 v1, v66
	v_mov_b32_e32 v2, v71
	v_mov_b32_e32 v3, v67
	global_store_dwordx4 v[8:9], v[0:3], off nt
	s_nop 1
	v_mov_b32_e32 v0, v64
	v_mov_b32_e32 v1, v36
	v_mov_b32_e32 v2, v65
	v_mov_b32_e32 v3, v37
	global_store_dwordx4 v[8:9], v[0:3], off offset:1024 nt
	s_nop 1
	v_mov_b32_e32 v0, v30
	v_mov_b32_e32 v1, v26
	v_mov_b32_e32 v2, v31
	v_mov_b32_e32 v3, v27
	global_store_dwordx4 v[8:9], v[0:3], off offset:2048 nt
	s_nop 1
	v_mov_b32_e32 v0, v22
	v_mov_b32_e32 v1, v16
	v_mov_b32_e32 v2, v23
	v_mov_b32_e32 v3, v17
	global_store_dwordx4 v[8:9], v[0:3], off offset:3072 nt
	s_nop 1
	v_mov_b32_e32 v0, v84
	v_mov_b32_e32 v1, v72
	v_mov_b32_e32 v2, v85
	v_mov_b32_e32 v3, v73
	global_store_dwordx4 v[4:5], v[0:3], off nt
	s_nop 1
	v_mov_b32_e32 v0, v42
	v_mov_b32_e32 v1, v38
	v_mov_b32_e32 v2, v43
	v_mov_b32_e32 v3, v39
	global_store_dwordx4 v[4:5], v[0:3], off offset:1024 nt
	s_nop 1
	v_mov_b32_e32 v0, v34
	v_mov_b32_e32 v1, v28
	v_mov_b32_e32 v2, v35
	v_mov_b32_e32 v3, v29
	global_store_dwordx4 v[4:5], v[0:3], off offset:2048 nt
	s_nop 1
	v_mov_b32_e32 v0, v14
	v_mov_b32_e32 v1, v18
	v_mov_b32_e32 v2, v15
	v_mov_b32_e32 v3, v19
	global_store_dwordx4 v[4:5], v[0:3], off offset:3072 nt
	s_cbranch_vccnz .LBB0_27
	v_mov_b32_e32 v4, v88
	v_mov_b32_e32 v5, v60
	v_mov_b32_e32 v2, v92
	v_mov_b32_e32 v3, v80
	v_pk_mul_f32 v[4:5], v[4:5], v[4:5]
	v_mov_b32_e32 v6, v40
	v_pk_fma_f32 v[2:3], v[2:3], v[2:3], v[4:5]
	v_mov_b32_e32 v4, v93
	v_mov_b32_e32 v5, v81
	v_pk_fma_f32 v[2:3], v[4:5], v[4:5], v[2:3]
	v_mov_b32_e32 v4, v89
	v_mov_b32_e32 v5, v61
	v_mov_b32_e32 v7, v12
	v_pk_fma_f32 v[2:3], v[4:5], v[4:5], v[2:3]
	v_mov_b32_e32 v4, v56
	v_mov_b32_e32 v5, v32
	v_pk_mul_f32 v[6:7], v[6:7], v[6:7]
	v_mov_b32_e32 v8, v82
	v_pk_fma_f32 v[4:5], v[4:5], v[4:5], v[6:7]
	v_mov_b32_e32 v6, v57
	v_mov_b32_e32 v7, v33
	v_pk_fma_f32 v[4:5], v[6:7], v[6:7], v[4:5]
	v_mov_b32_e32 v6, v41
	v_mov_b32_e32 v7, v13
	v_mov_b32_e32 v9, v74
	v_pk_fma_f32 v[4:5], v[6:7], v[6:7], v[4:5]
	v_mov_b32_e32 v6, v86
	v_mov_b32_e32 v7, v78
	v_pk_mul_f32 v[8:9], v[8:9], v[8:9]
	v_mov_b32_e32 v10, v48
	v_pk_fma_f32 v[6:7], v[6:7], v[6:7], v[8:9]
	v_mov_b32_e32 v8, v87
	v_mov_b32_e32 v9, v79
	v_pk_fma_f32 v[6:7], v[8:9], v[8:9], v[6:7]
	v_mov_b32_e32 v8, v83
	v_mov_b32_e32 v9, v75
	v_mov_b32_e32 v11, v20
	v_pk_fma_f32 v[6:7], v[8:9], v[8:9], v[6:7]
	v_mov_b32_e32 v8, v52
	v_mov_b32_e32 v9, v24
	v_pk_mul_f32 v[10:11], v[10:11], v[10:11]
	s_mov_b32 s0, 0x358637bd
	v_pk_fma_f32 v[8:9], v[8:9], v[8:9], v[10:11]
	v_mov_b32_e32 v10, v53
	v_mov_b32_e32 v11, v25
	v_pk_fma_f32 v[8:9], v[10:11], v[10:11], v[8:9]
	v_mov_b32_e32 v10, v49
	v_mov_b32_e32 v11, v21
	v_pk_fma_f32 v[8:9], v[10:11], v[10:11], v[8:9]
	v_mov_b32_e32 v10, v6
	v_mov_b32_e32 v11, v2
	v_mov_b32_e32 v2, v7
	v_pk_add_f32 v[2:3], v[10:11], v[2:3]
	v_mov_b32_e32 v6, v8
	v_mov_b32_e32 v7, v4
	v_pk_add_f32 v[2:3], v[2:3], v[6:7]
	v_mov_b32_e32 v4, v9
	v_pk_add_f32 v[2:3], v[2:3], v[4:5]
	ds_bpermute_b32 v5, v107, v3
	ds_bpermute_b32 v4, v107, v2
	s_mov_b32 s14, 0x3a800000
	s_mov_b32 s12, 0x800000
	v_mov_b32_e32 v7, v36
	v_mov_b32_e32 v8, v26
	s_waitcnt lgkmcnt(0)
	v_pk_add_f32 v[2:3], v[2:3], v[4:5]
	ds_bpermute_b32 v5, v109, v3
	ds_bpermute_b32 v4, v109, v2
	v_mov_b32_e32 v9, v16
	v_pk_mul_f32 v[8:9], v[8:9], v[8:9]
	v_mov_b32_e32 v10, v72
	v_mov_b32_e32 v11, v38
	s_waitcnt lgkmcnt(0)
	v_pk_add_f32 v[2:3], v[2:3], v[4:5]
	ds_bpermute_b32 v5, v111, v3
	ds_bpermute_b32 v4, v111, v2
	v_pk_mul_f32 v[10:11], v[10:11], v[10:11]
	v_mov_b32_e32 v50, v28
	v_mov_b32_e32 v51, v18
	v_pk_mul_f32 v[50:51], v[50:51], v[50:51]
	s_waitcnt lgkmcnt(0)
	v_pk_add_f32 v[2:3], v[2:3], v[4:5]
	ds_bpermute_b32 v5, v169, v3
	ds_bpermute_b32 v4, v169, v2
	v_add_u32_e32 v0, v172, v168
	v_mul_hi_i32_i24_e32 v1, 0x6000, v0
	v_mul_i32_i24_e32 v0, 0x6000, v0
	v_lshl_add_u64 v[0:1], s[96:97], 0, v[0:1]
	s_waitcnt lgkmcnt(0)
	v_pk_add_f32 v[2:3], v[2:3], v[4:5]
	ds_bpermute_b32 v5, v170, v3
	ds_bpermute_b32 v4, v170, v2
	v_lshl_add_u64 v[62:63], v[0:1], 0, v[192:193]
	v_lshl_add_u64 v[58:59], v[102:103], 0, v[118:119]
	s_waitcnt lgkmcnt(0)
	v_pk_add_f32 v[2:3], v[2:3], v[4:5]
	ds_bpermute_b32 v5, v171, v3
	ds_bpermute_b32 v4, v171, v2
	s_waitcnt lgkmcnt(0)
	v_pk_add_f32 v[2:3], v[2:3], v[4:5]
	v_mov_b64_e32 v[4:5], s[0:1]
	v_pk_fma_f32 v[2:3], v[2:3], s[14:15], v[4:5] op_sel_hi:[1,0,0]
	s_nop 0
	v_mul_f32_e32 v6, 0x4b800000, v3
	v_cmp_gt_f32_e64 s[0:1], s12, v3
	v_cmp_gt_f32_e32 vcc, s12, v2
	s_nop 0
	v_cndmask_b32_e64 v3, v3, v6, s[0:1]
	v_rsq_f32_e32 v3, v3
	s_nop 0
	v_mul_f32_e32 v6, 0x45800000, v3
	v_cndmask_b32_e64 v46, v3, v6, s[0:1]
	v_mul_f32_e32 v3, 0x4b800000, v2
	v_cndmask_b32_e32 v2, v2, v3, vcc
	v_rsq_f32_e32 v2, v2
	v_mov_b32_e32 v6, v66
	v_pk_mul_f32 v[6:7], v[6:7], v[6:7]
	v_pk_mul_f32 v[88:89], v[88:89], v[46:47] op_sel_hi:[1,0]
	v_mul_f32_e32 v3, 0x45800000, v2
	v_cndmask_b32_e32 v44, v2, v3, vcc
	v_mov_b32_e32 v2, v70
	v_mov_b32_e32 v3, v64
	v_pk_fma_f32 v[2:3], v[2:3], v[2:3], v[6:7]
	v_mov_b32_e32 v6, v71
	v_mov_b32_e32 v7, v65
	v_pk_fma_f32 v[2:3], v[6:7], v[6:7], v[2:3]
	v_mov_b32_e32 v6, v67
	v_mov_b32_e32 v7, v37
	v_pk_fma_f32 v[2:3], v[6:7], v[6:7], v[2:3]
	v_mov_b32_e32 v6, v30
	v_mov_b32_e32 v7, v22
	v_pk_fma_f32 v[6:7], v[6:7], v[6:7], v[8:9]
	v_mov_b32_e32 v8, v31
	v_mov_b32_e32 v9, v23
	v_pk_fma_f32 v[6:7], v[8:9], v[8:9], v[6:7]
	v_mov_b32_e32 v8, v27
	v_mov_b32_e32 v9, v17
	v_pk_fma_f32 v[6:7], v[8:9], v[8:9], v[6:7]
	v_mov_b32_e32 v8, v84
	v_mov_b32_e32 v9, v42
	v_pk_fma_f32 v[8:9], v[8:9], v[8:9], v[10:11]
	v_mov_b32_e32 v10, v85
	v_mov_b32_e32 v11, v43
	v_pk_fma_f32 v[8:9], v[10:11], v[10:11], v[8:9]
	v_mov_b32_e32 v10, v73
	v_mov_b32_e32 v11, v39
	v_pk_fma_f32 v[8:9], v[10:11], v[10:11], v[8:9]
	v_mov_b32_e32 v10, v34
	v_mov_b32_e32 v11, v14
	v_pk_fma_f32 v[10:11], v[10:11], v[10:11], v[50:51]
	v_mov_b32_e32 v50, v35
	v_mov_b32_e32 v51, v15
	v_pk_fma_f32 v[10:11], v[50:51], v[50:51], v[10:11]
	v_mov_b32_e32 v50, v29
	v_mov_b32_e32 v51, v19
	v_pk_fma_f32 v[10:11], v[50:51], v[50:51], v[10:11]
	v_mov_b32_e32 v50, v8
	v_mov_b32_e32 v51, v2
	v_mov_b32_e32 v2, v9
	v_pk_add_f32 v[2:3], v[50:51], v[2:3]
	v_mov_b32_e32 v8, v10
	v_mov_b32_e32 v9, v6
	v_pk_add_f32 v[2:3], v[2:3], v[8:9]
	v_mov_b32_e32 v6, v11
	v_pk_add_f32 v[2:3], v[2:3], v[6:7]
	ds_bpermute_b32 v7, v107, v3
	ds_bpermute_b32 v6, v107, v2
	v_mov_b32_e32 v107, v193
	s_waitcnt lgkmcnt(0)
	v_pk_add_f32 v[2:3], v[2:3], v[6:7]
	ds_bpermute_b32 v7, v109, v3
	ds_bpermute_b32 v6, v109, v2
	v_mov_b32_e32 v109, v193
	s_waitcnt lgkmcnt(0)
	v_pk_add_f32 v[2:3], v[2:3], v[6:7]
	ds_bpermute_b32 v7, v111, v3
	ds_bpermute_b32 v6, v111, v2
	v_mov_b32_e32 v111, v193
	s_waitcnt lgkmcnt(0)
	v_pk_add_f32 v[2:3], v[2:3], v[6:7]
	ds_bpermute_b32 v7, v169, v3
	ds_bpermute_b32 v6, v169, v2
	s_waitcnt lgkmcnt(0)
	v_pk_add_f32 v[2:3], v[2:3], v[6:7]
	ds_bpermute_b32 v7, v170, v3
	ds_bpermute_b32 v6, v170, v2
	s_waitcnt lgkmcnt(0)
	v_pk_add_f32 v[2:3], v[2:3], v[6:7]
	ds_bpermute_b32 v7, v171, v3
	ds_bpermute_b32 v6, v171, v2
	s_waitcnt lgkmcnt(0)
	v_pk_add_f32 v[2:3], v[2:3], v[6:7]
	s_nop 0
	v_pk_fma_f32 v[2:3], v[2:3], s[14:15], v[4:5] op_sel_hi:[1,0,0]
	s_nop 0
	v_mul_f32_e32 v4, 0x4b800000, v3
	v_cmp_gt_f32_e64 s[0:1], s12, v3
	v_cmp_gt_f32_e32 vcc, s12, v2
	s_nop 0
	v_cndmask_b32_e64 v3, v3, v4, s[0:1]
	v_rsq_f32_e32 v3, v3
	s_nop 0
	v_mul_f32_e32 v4, 0x45800000, v3
	v_cndmask_b32_e64 v54, v3, v4, s[0:1]
	v_mul_f32_e32 v3, 0x4b800000, v2
	v_cndmask_b32_e32 v2, v2, v3, vcc
	v_rsq_f32_e32 v2, v2
	s_mov_b64 s[0:1], 0x1000
	v_lshl_add_u64 v[68:69], v[0:1], 0, s[0:1]
	v_lshl_add_u64 v[4:5], v[68:69], 0, v[192:193]
	v_mul_f32_e32 v3, 0x45800000, v2
	v_cndmask_b32_e32 v50, v2, v3, vcc
	global_load_dwordx4 v[0:3], v[100:101], off
	global_load_dwordx4 v[8:11], v[4:5], off
	s_nop 0
	global_load_dwordx4 v[4:7], v[62:63], off
	v_pk_mul_f32 v[66:67], v[66:67], v[54:55] op_sel_hi:[1,0]
	v_pk_mul_f32 v[36:37], v[36:37], v[54:55] op_sel_hi:[1,0]
	v_pk_mul_f32 v[26:27], v[26:27], v[54:55] op_sel_hi:[1,0]
	s_waitcnt vmcnt(2)
	v_mov_b32_e32 v90, v0
	s_waitcnt vmcnt(1)
	v_mov_b32_e32 v76, v8
	v_mov_b32_e32 v77, v10
	v_mov_b32_e32 v10, v9
	v_pk_mul_f32 v[8:9], v[92:93], v[46:47] op_sel_hi:[1,0]
	v_mov_b32_e32 v91, v2
	v_pk_add_f32 v[76:77], v[76:77], 1.0 op_sel_hi:[1,0]
	v_pk_mul_f32 v[8:9], v[8:9], v[90:91]
	s_waitcnt vmcnt(0)
	v_mov_b32_e32 v92, v4
	v_mov_b32_e32 v93, v6
	v_mov_b32_e32 v2, v1
	v_pk_add_f32 v[10:11], v[10:11], 1.0 op_sel_hi:[1,0]
	v_pk_fma_f32 v[8:9], v[8:9], v[76:77], v[92:93]
	v_pk_mul_f32 v[0:1], v[88:89], v[2:3]
	v_mov_b32_e32 v6, v5
	v_pk_fma_f32 v[0:1], v[0:1], v[10:11], v[6:7]
	v_cvt_pk_bf16_f32 v0, v8, v0
	v_cvt_pk_bf16_f32 v1, v9, v1
	v_pk_mul_f32 v[4:5], v[86:87], v[44:45] op_sel_hi:[1,0]
	v_pk_mul_f32 v[8:9], v[82:83], v[44:45] op_sel_hi:[1,0]
	v_pk_mul_f32 v[4:5], v[4:5], v[90:91]
	v_pk_mul_f32 v[8:9], v[8:9], v[2:3]
	v_pk_fma_f32 v[4:5], v[4:5], v[76:77], v[92:93]
	v_pk_fma_f32 v[8:9], v[8:9], v[10:11], v[6:7]
	v_cvt_pk_bf16_f32 v5, v5, v9
	v_cvt_pk_bf16_f32 v4, v4, v8
	v_pk_mul_f32 v[8:9], v[70:71], v[54:55] op_sel_hi:[1,0]
	v_pk_mul_f32 v[66:67], v[2:3], v[66:67]
	v_pk_mul_f32 v[8:9], v[90:91], v[8:9]
	v_pk_fma_f32 v[66:67], v[66:67], v[10:11], v[6:7]
	v_pk_fma_f32 v[8:9], v[8:9], v[76:77], v[92:93]
	v_pk_mul_f32 v[70:71], v[72:73], v[50:51] op_sel_hi:[1,0]
	v_cvt_pk_bf16_f32 v9, v9, v67
	v_and_b32_sdwa v47, v8, v218 dst_sel:DWORD dst_unused:UNUSED_PAD src0_sel:WORD_1 src1_sel:DWORD
	v_add3_u32 v8, v8, v47, s80
	v_and_b32_sdwa v47, v66, v218 dst_sel:DWORD dst_unused:UNUSED_PAD src0_sel:WORD_1 src1_sel:DWORD
	v_add3_u32 v47, v66, v47, s80
	v_pk_mul_f32 v[66:67], v[84:85], v[50:51] op_sel_hi:[1,0]
	v_pk_mul_f32 v[2:3], v[2:3], v[70:71]
	v_pk_mul_f32 v[66:67], v[90:91], v[66:67]
	v_pk_fma_f32 v[2:3], v[10:11], v[2:3], v[6:7]
	v_pk_fma_f32 v[66:67], v[76:77], v[66:67], v[92:93]
	global_store_dwordx2 v[58:59], v[0:1], off nt
	v_lshl_add_u64 v[0:1], v[102:103], 0, v[116:117]
	v_and_b32_e32 v47, 0xffff0000, v47
	v_cvt_pk_bf16_f32 v3, v67, v3
	v_cvt_pk_bf16_f32 v2, v66, v2
	global_store_dwordx2 v[0:1], v[4:5], off nt
	v_lshl_add_u64 v[4:5], v[102:103], 0, v[114:115]
	v_or_b32_sdwa v8, v47, v8 dst_sel:DWORD dst_unused:UNUSED_PAD src0_sel:DWORD src1_sel:WORD_1
	global_store_dwordx2 v[4:5], v[8:9], off nt
	v_lshl_add_u64 v[8:9], v[102:103], 0, v[112:113]
	global_store_dwordx2 v[8:9], v[2:3], off nt
	v_lshl_add_u64 v[2:3], v[68:69], 0, v[106:107]
	global_load_dwordx4 v[70:73], v[100:101], off offset:1024
	global_load_dwordx4 v[82:85], v[2:3], off
	global_load_dwordx4 v[86:89], v[62:63], off offset:1024
	v_pk_mul_f32 v[10:11], v[80:81], v[46:47] op_sel_hi:[1,0]
	v_pk_mul_f32 v[60:61], v[60:61], v[46:47] op_sel_hi:[1,0]
	s_waitcnt vmcnt(2)
	v_mov_b32_e32 v66, v70
	s_waitcnt vmcnt(1)
	v_mov_b32_e32 v2, v82
	v_mov_b32_e32 v3, v84
	v_mov_b32_e32 v67, v72
	v_pk_add_f32 v[2:3], v[2:3], 1.0 op_sel_hi:[1,0]
	v_mov_b32_e32 v84, v83
	v_pk_mul_f32 v[10:11], v[10:11], v[66:67]
	s_waitcnt vmcnt(0)
	v_mov_b32_e32 v76, v86
	v_mov_b32_e32 v77, v88
	v_mov_b32_e32 v72, v71
	v_pk_add_f32 v[6:7], v[84:85], 1.0 op_sel_hi:[1,0]
	v_pk_fma_f32 v[10:11], v[10:11], v[2:3], v[76:77]
	v_pk_mul_f32 v[60:61], v[60:61], v[72:73]
	v_mov_b32_e32 v88, v87
	v_pk_fma_f32 v[60:61], v[60:61], v[6:7], v[88:89]
	v_and_b32_sdwa v45, v11, v218 dst_sel:DWORD dst_unused:UNUSED_PAD src0_sel:WORD_1 src1_sel:DWORD
	v_cvt_pk_bf16_f32 v10, v10, v60
	v_add3_u32 v11, v11, v45, s80
	v_and_b32_sdwa v45, v61, v218 dst_sel:DWORD dst_unused:UNUSED_PAD src0_sel:WORD_1 src1_sel:DWORD
	v_add3_u32 v45, v61, v45, s80
	v_and_b32_e32 v45, 0xffff0000, v45
	v_or_b32_sdwa v11, v45, v11 dst_sel:DWORD dst_unused:UNUSED_PAD src0_sel:DWORD src1_sel:WORD_1
	global_store_dwordx2 v[58:59], v[10:11], off offset:512 nt
	v_pk_mul_f32 v[10:11], v[78:79], v[44:45] op_sel_hi:[1,0]
	v_pk_mul_f32 v[60:61], v[74:75], v[44:45] op_sel_hi:[1,0]
	v_pk_mul_f32 v[10:11], v[10:11], v[66:67]
	v_pk_mul_f32 v[60:61], v[60:61], v[72:73]
	v_pk_fma_f32 v[10:11], v[10:11], v[2:3], v[76:77]
	v_pk_fma_f32 v[60:61], v[60:61], v[6:7], v[88:89]
	v_cvt_pk_bf16_f32 v11, v11, v61
	v_cvt_pk_bf16_f32 v10, v10, v60
	global_store_dwordx2 v[0:1], v[10:11], off offset:512 nt
	v_pk_mul_f32 v[10:11], v[64:65], v[54:55] op_sel_hi:[1,0]
	v_pk_mul_f32 v[36:37], v[36:37], v[72:73]
	v_pk_mul_f32 v[10:11], v[10:11], v[66:67]
	v_pk_fma_f32 v[36:37], v[36:37], v[6:7], v[88:89]
	v_pk_fma_f32 v[10:11], v[10:11], v[2:3], v[76:77]
	s_nop 0
	v_and_b32_sdwa v45, v11, v218 dst_sel:DWORD dst_unused:UNUSED_PAD src0_sel:WORD_1 src1_sel:DWORD
	v_and_b32_sdwa v47, v10, v218 dst_sel:DWORD dst_unused:UNUSED_PAD src0_sel:WORD_1 src1_sel:DWORD
	v_add3_u32 v10, v10, v47, s80
	v_add3_u32 v11, v11, v45, s80
	v_and_b32_sdwa v45, v37, v218 dst_sel:DWORD dst_unused:UNUSED_PAD src0_sel:WORD_1 src1_sel:DWORD
	v_and_b32_sdwa v47, v36, v218 dst_sel:DWORD dst_unused:UNUSED_PAD src0_sel:WORD_1 src1_sel:DWORD
	v_add3_u32 v37, v37, v45, s80
	v_add3_u32 v36, v36, v47, s80
	v_and_b32_e32 v37, 0xffff0000, v37
	v_and_b32_e32 v36, 0xffff0000, v36
	v_or_b32_sdwa v11, v37, v11 dst_sel:DWORD dst_unused:UNUSED_PAD src0_sel:DWORD src1_sel:WORD_1
	v_or_b32_sdwa v10, v36, v10 dst_sel:DWORD dst_unused:UNUSED_PAD src0_sel:DWORD src1_sel:WORD_1
	global_store_dwordx2 v[4:5], v[10:11], off offset:512 nt
	v_pk_mul_f32 v[10:11], v[42:43], v[50:51] op_sel_hi:[1,0]
	v_pk_mul_f32 v[40:41], v[40:41], v[46:47] op_sel_hi:[1,0]
	v_pk_mul_f32 v[10:11], v[10:11], v[66:67]
	v_pk_mul_f32 v[12:13], v[12:13], v[46:47] op_sel_hi:[1,0]
	v_pk_fma_f32 v[2:3], v[10:11], v[2:3], v[76:77]
	v_pk_mul_f32 v[10:11], v[38:39], v[50:51] op_sel_hi:[1,0]
	s_nop 0
	v_pk_mul_f32 v[10:11], v[10:11], v[72:73]
	s_nop 0
	v_pk_fma_f32 v[6:7], v[10:11], v[6:7], v[88:89]
	v_cvt_pk_bf16_f32 v3, v3, v7
	v_cvt_pk_bf16_f32 v2, v2, v6
	global_store_dwordx2 v[8:9], v[2:3], off offset:512 nt
	v_lshl_add_u64 v[2:3], v[68:69], 0, v[108:109]
	global_load_dwordx4 v[36:39], v[100:101], off offset:2048
	global_load_dwordx4 v[64:67], v[2:3], off
	global_load_dwordx4 v[70:73], v[62:63], off offset:2048
	v_pk_mul_f32 v[10:11], v[56:57], v[46:47] op_sel_hi:[1,0]
	s_waitcnt vmcnt(2)
	v_mov_b32_e32 v42, v36
	s_waitcnt vmcnt(1)
	v_mov_b32_e32 v2, v64
	v_mov_b32_e32 v3, v66
	v_mov_b32_e32 v43, v38
	v_pk_add_f32 v[2:3], v[2:3], 1.0 op_sel_hi:[1,0]
	v_mov_b32_e32 v66, v65
	v_pk_mul_f32 v[10:11], v[10:11], v[42:43]
	s_waitcnt vmcnt(0)
	v_mov_b32_e32 v56, v70
	v_mov_b32_e32 v57, v72
	v_mov_b32_e32 v38, v37
	v_pk_add_f32 v[6:7], v[66:67], 1.0 op_sel_hi:[1,0]
	v_pk_fma_f32 v[10:11], v[10:11], v[2:3], v[56:57]
	v_pk_mul_f32 v[36:37], v[40:41], v[38:39]
	v_mov_b32_e32 v72, v71
	v_pk_fma_f32 v[36:37], v[36:37], v[6:7], v[72:73]
	v_cvt_pk_bf16_f32 v11, v11, v37
	v_cvt_pk_bf16_f32 v10, v10, v36
	global_store_dwordx2 v[58:59], v[10:11], off offset:1024 nt
	v_pk_mul_f32 v[10:11], v[52:53], v[44:45] op_sel_hi:[1,0]
	v_pk_mul_f32 v[36:37], v[48:49], v[44:45] op_sel_hi:[1,0]
	v_pk_mul_f32 v[10:11], v[10:11], v[42:43]
	v_pk_mul_f32 v[36:37], v[36:37], v[38:39]
	v_pk_fma_f32 v[10:11], v[10:11], v[2:3], v[56:57]
	v_pk_fma_f32 v[36:37], v[36:37], v[6:7], v[72:73]
	v_cvt_pk_bf16_f32 v11, v11, v37
	v_cvt_pk_bf16_f32 v10, v10, v36
	global_store_dwordx2 v[0:1], v[10:11], off offset:1024 nt
	v_pk_mul_f32 v[10:11], v[30:31], v[54:55] op_sel_hi:[1,0]
	v_pk_mul_f32 v[26:27], v[26:27], v[38:39]
	v_pk_mul_f32 v[10:11], v[10:11], v[42:43]
	v_pk_fma_f32 v[26:27], v[26:27], v[6:7], v[72:73]
	v_pk_fma_f32 v[10:11], v[10:11], v[2:3], v[56:57]
	s_nop 0
	v_cvt_pk_bf16_f32 v11, v11, v27
	v_cvt_pk_bf16_f32 v10, v10, v26
	global_store_dwordx2 v[4:5], v[10:11], off offset:1024 nt
	v_pk_mul_f32 v[10:11], v[34:35], v[50:51] op_sel_hi:[1,0]
	s_nop 0
	v_pk_mul_f32 v[10:11], v[10:11], v[42:43]
	s_nop 0
	v_pk_fma_f32 v[2:3], v[10:11], v[2:3], v[56:57]
	v_pk_mul_f32 v[10:11], v[28:29], v[50:51] op_sel_hi:[1,0]
	s_nop 0
	v_pk_mul_f32 v[10:11], v[10:11], v[38:39]
	s_nop 0
	v_pk_fma_f32 v[6:7], v[10:11], v[6:7], v[72:73]
	v_cvt_pk_bf16_f32 v3, v3, v7
	v_cvt_pk_bf16_f32 v2, v2, v6
	global_store_dwordx2 v[8:9], v[2:3], off offset:1024 nt
	v_lshl_add_u64 v[2:3], v[68:69], 0, v[110:111]
	global_load_dwordx4 v[26:29], v[100:101], off offset:3072
	global_load_dwordx4 v[34:37], v[2:3], off
	global_load_dwordx4 v[38:41], v[62:63], off offset:3072
	v_pk_mul_f32 v[10:11], v[32:33], v[46:47] op_sel_hi:[1,0]
	s_waitcnt vmcnt(2)
	v_mov_b32_e32 v30, v26
	s_waitcnt vmcnt(1)
	v_mov_b32_e32 v2, v34
	v_mov_b32_e32 v3, v36
	v_mov_b32_e32 v31, v28
	v_pk_add_f32 v[2:3], v[2:3], 1.0 op_sel_hi:[1,0]
	v_mov_b32_e32 v36, v35
	v_pk_mul_f32 v[10:11], v[10:11], v[30:31]
	s_waitcnt vmcnt(0)
	v_mov_b32_e32 v32, v38
	v_mov_b32_e32 v33, v40
	v_mov_b32_e32 v28, v27
	v_pk_add_f32 v[6:7], v[36:37], 1.0 op_sel_hi:[1,0]
	v_pk_fma_f32 v[10:11], v[10:11], v[2:3], v[32:33]
	v_pk_mul_f32 v[12:13], v[12:13], v[28:29]
	v_mov_b32_e32 v40, v39
	v_pk_fma_f32 v[12:13], v[12:13], v[6:7], v[40:41]
	v_cvt_pk_bf16_f32 v11, v11, v13
	v_cvt_pk_bf16_f32 v10, v10, v12
	global_store_dwordx2 v[58:59], v[10:11], off offset:1536 nt
	v_pk_mul_f32 v[10:11], v[24:25], v[44:45] op_sel_hi:[1,0]
	v_pk_mul_f32 v[12:13], v[20:21], v[44:45] op_sel_hi:[1,0]
	v_pk_mul_f32 v[10:11], v[10:11], v[30:31]
	v_pk_mul_f32 v[12:13], v[12:13], v[28:29]
	v_pk_fma_f32 v[10:11], v[10:11], v[2:3], v[32:33]
	v_pk_fma_f32 v[12:13], v[12:13], v[6:7], v[40:41]
	v_cvt_pk_bf16_f32 v11, v11, v13
	v_cvt_pk_bf16_f32 v10, v10, v12
	global_store_dwordx2 v[0:1], v[10:11], off offset:1536 nt
	v_pk_mul_f32 v[0:1], v[22:23], v[54:55] op_sel_hi:[1,0]
	v_pk_mul_f32 v[10:11], v[16:17], v[54:55] op_sel_hi:[1,0]
	v_pk_mul_f32 v[0:1], v[0:1], v[30:31]
	v_pk_mul_f32 v[10:11], v[10:11], v[28:29]
	v_pk_fma_f32 v[0:1], v[0:1], v[2:3], v[32:33]
	v_pk_fma_f32 v[10:11], v[10:11], v[6:7], v[40:41]
	v_cvt_pk_bf16_f32 v1, v1, v11
	v_cvt_pk_bf16_f32 v0, v0, v10
	global_store_dwordx2 v[4:5], v[0:1], off offset:1536 nt
	v_pk_mul_f32 v[0:1], v[14:15], v[50:51] op_sel_hi:[1,0]
	s_nop 0
	v_pk_mul_f32 v[0:1], v[0:1], v[30:31]
	s_nop 0
	v_pk_fma_f32 v[0:1], v[0:1], v[2:3], v[32:33]
	v_pk_mul_f32 v[2:3], v[18:19], v[50:51] op_sel_hi:[1,0]
	v_and_b32_sdwa v4, v1, v218 dst_sel:DWORD dst_unused:UNUSED_PAD src0_sel:WORD_1 src1_sel:DWORD
	v_pk_mul_f32 v[2:3], v[2:3], v[28:29]
	v_and_b32_sdwa v5, v0, v218 dst_sel:DWORD dst_unused:UNUSED_PAD src0_sel:WORD_1 src1_sel:DWORD
	v_pk_fma_f32 v[2:3], v[2:3], v[6:7], v[40:41]
	v_add3_u32 v0, v0, v5, s80
	v_add3_u32 v1, v1, v4, s80
	v_and_b32_sdwa v4, v3, v218 dst_sel:DWORD dst_unused:UNUSED_PAD src0_sel:WORD_1 src1_sel:DWORD
	v_and_b32_sdwa v5, v2, v218 dst_sel:DWORD dst_unused:UNUSED_PAD src0_sel:WORD_1 src1_sel:DWORD
	v_add3_u32 v3, v3, v4, s80
	v_add3_u32 v2, v2, v5, s80
	v_and_b32_e32 v3, 0xffff0000, v3
	v_and_b32_e32 v2, 0xffff0000, v2
	v_or_b32_sdwa v1, v3, v1 dst_sel:DWORD dst_unused:UNUSED_PAD src0_sel:DWORD src1_sel:WORD_1
	v_or_b32_sdwa v0, v2, v0 dst_sel:DWORD dst_unused:UNUSED_PAD src0_sel:DWORD src1_sel:WORD_1
	global_store_dwordx2 v[8:9], v[0:1], off offset:1536 nt
	s_branch .LBB0_27
